# baseline (speedup 1.0000x reference)
; __device__ __forceinline__ void xcd_share(int ntiles, int& start, int& j, int& per, int& cnt) {
;   const int G = gridDim.x, b = blockIdx.x;
;   if ((G & 7) == 0) {
;     int xcd = b & 7;
;     j = b >> 3;
;     per = G >> 3;
;     int q = ntiles >> 3, r = ntiles & 7;
;     start = xcd < r ? xcd * (q + 1) : r * (q + 1) + (xcd - r) * q;
;     cnt = q + (xcd < r ? 1 : 0);
;   } else {
;     start = 0;
;     cnt = ntiles;
;     j = b;
;     per = G;
;   }
; }
; template <int EPI> ...
;   int startA, jA, perA, cntA;
;   xcd_share(nM * nN, startA, jA, perA, cntA);
;   const int nA = jA < cntA ? (cntA - jA + perA - 1) / perA : 0;
.LBB0_175:
	v_readlane_b32 s1, v255, 9
	v_readlane_b32 s0, v255, 8
	v_readlane_b32 s2, v255, 7
	s_nop 1
	s_mul_i32 s1, s1, s0
	s_add_i32 s1, s1, s2
	s_mov_b32 s0, 0
	s_mov_b32 s94, s3
	s_lshl_b32 s2, s77, 3
	s_cmp_ge_i32 s1, s2
	s_cbranch_scc0 .LBB0_170
	s_branch .LBB0_171

; template <int EPI> ...
;     ...
;   auto tile_desc = [&](int i, int& pm, int& pn, int& koff, bool& atom) {
;     koff = 0;
;     atom = false;
;     if (i < nA) {
;       tile_coords(startA + jA + i * perA, nM, nN, pm, pn);
;     } else {
;       int u = startB + jB + (i - nA) * perB;
;       pm = mini_pm;
;       pn = u % nN;
;       koff = (u / nN) * Kc;
;       atom = true;
;     }
;   };
.LBB0_182:
	s_cmp_ge_i32 s99, s95
	s_cselect_b64 s[82:83], -1, 0
	s_cmp_lt_i32 s99, s95
	s_mov_b64 s[40:41], -1
	s_cselect_b64 s[84:85], -1, 0
	s_and_b64 vcc, exec, s[82:83]
	s_cbranch_vccnz .LBB0_184
	s_mul_i32 s2, s99, s94
	s_add_i32 s2, s2, s58
	s_ashr_i32 s6, s2, 31
	s_lshr_b32 s6, s6, 26
	s_add_i32 s6, s2, s6
	s_ashr_i32 s7, s6, 6
	s_lshl_b32 s7, s7, 3
	s_sub_i32 s8, s77, s7
	s_min_i32 s8, s8, 8
	s_abs_i32 s9, s8
	v_cvt_f32_u32_e32 v0, s9
	s_sub_i32 s11, 0, s9
	s_andn2_b32 s6, s6, 63
	s_sub_i32 s6, s2, s6
	v_rcp_iflag_f32_e32 v0, v0
	s_abs_i32 s2, s6
	s_xor_b32 s10, s6, s8
	s_ashr_i32 s10, s10, 31
	v_mul_f32_e32 v0, 0x4f7ffffe, v0
	v_cvt_u32_f32_e32 v0, v0
	s_mov_b64 s[40:41], 0
	v_readfirstlane_b32 s20, v0
	s_mul_i32 s11, s11, s20
	s_mul_hi_u32 s11, s20, s11
	s_add_i32 s20, s20, s11
	s_mul_hi_u32 s11, s2, s20
	s_mul_i32 s20, s11, s9
	s_sub_i32 s2, s2, s20
	s_add_i32 s21, s11, 1
	s_sub_i32 s20, s2, s9
	s_cmp_ge_u32 s2, s9
	s_cselect_b32 s11, s21, s11
	s_cselect_b32 s2, s20, s2
	s_add_i32 s20, s11, 1
	s_cmp_ge_u32 s2, s9
	s_cselect_b32 s2, s20, s11
	s_xor_b32 s2, s2, s10
	s_sub_i32 s2, s2, s10
	s_mul_i32 s8, s2, s8
	s_sub_i32 s6, s6, s8
	s_add_i32 s7, s6, s7
	s_sub_i32 s7, s77, s7
	s_add_i32 s7, s7, -1

; template <int EPI> ...
;     ...
;   auto tile_desc = [&](int i, int& pm, int& pn, int& koff, bool& atom) {
;     koff = 0;
;     atom = false;
;     if (i < nA) {
;       tile_coords(startA + jA + i * perA, nM, nN, pm, pn);
;     } else {
;       int u = startB + jB + (i - nA) * perB;
;       pm = mini_pm;
;       pn = u % nN;
;       koff = (u / nN) * Kc;
;       atom = true;
;     }
;   };
.LBB0_191:
	s_andn2_b64 vcc, exec, s[50:51]
	s_mov_b32 s8, s56
	s_cbranch_vccnz .LBB0_193
	s_mul_i32 s7, s99, s94
	s_add_i32 s7, s7, s58
	s_ashr_i32 s8, s7, 31
	s_lshr_b32 s8, s8, 26
	s_add_i32 s8, s7, s8
	s_ashr_i32 s9, s8, 6
	s_lshl_b32 s9, s9, 3
	s_sub_i32 s10, s77, s9
	s_min_i32 s10, s10, 8
	s_abs_i32 s11, s10
	v_cvt_f32_u32_e32 v0, s11
	s_sub_i32 s21, 0, s11
	s_andn2_b32 s8, s8, 63
	s_sub_i32 s8, s7, s8
	v_rcp_iflag_f32_e32 v0, v0
	s_abs_i32 s7, s8
	s_xor_b32 s20, s8, s10
	s_ashr_i32 s20, s20, 31
	v_mul_f32_e32 v0, 0x4f7ffffe, v0
	v_cvt_u32_f32_e32 v0, v0
	s_mov_b64 s[40:41], 0
	v_readfirstlane_b32 s28, v0
	s_mul_i32 s21, s21, s28
	s_mul_hi_u32 s21, s28, s21
	s_add_i32 s28, s28, s21
	s_mul_hi_u32 s21, s7, s28
	s_mul_i32 s28, s21, s11
	s_sub_i32 s7, s7, s28
	s_add_i32 s29, s21, 1
	s_sub_i32 s28, s7, s11
	s_cmp_ge_u32 s7, s11
	s_cselect_b32 s21, s29, s21
	s_cselect_b32 s7, s28, s7
	s_add_i32 s28, s21, 1
	s_cmp_ge_u32 s7, s11
	s_cselect_b32 s7, s28, s21
	s_xor_b32 s7, s7, s20
	s_sub_i32 s7, s7, s20
	s_mul_i32 s10, s7, s10
	s_sub_i32 s8, s8, s10
	s_add_i32 s8, s8, s9
	s_sub_i32 s8, s77, s8
	s_add_i32 s8, s8, -1
